# Toeplitz fill: dropped the vmcnt(0) at the head of the diagonal path (it only waited for loads of other lanes); counted waits after it already cover the path's own loads
# speedup vs baseline: 1.0052x; 1.0016x over previous
; __device__ __forceinline__ void toeplitz_fill(KArgs& a, int l) {
;     ...
;         const int k8 = (int)(e & 63), row = (int)((e >> 6) & 511), gI = (int)(e >> 15);
;         const int t = row >> 4, n = row & 15, s = k8 >> 1, m0 = (k8 & 1) * 8;
;         float v[8];
;         if (s == t) {
;             const float* kf = KT + ((((size_t)gI * 2 + 0) * 32 + 0) * 16 + n) * 16 + m0; const float* kb = KT + ((((size_t)gI * 2 + 1) * 32 + 0) * 16 + n) * 16 + m0;
; #pragma unroll
;             for (int i = 0; i < 8; ++i) v[i] = kf[i] + kb[i] + ((m0 + i) == n ? dsk[gI * 16 + n] : 0.f);
.LBB0_350:
	s_andn2_saveexec_b64 s[22:23], s[22:23]
	s_cbranch_execz .LBB0_347
	v_lshlrev_b64 v[2:3], 16, v[14:15]
	v_lshl_add_u64 v[2:3], s[14:15], 0, v[2:3]
	v_lshl_add_u64 v[2:3], v[2:3], 0, v[0:1]
	v_mov_b32_e32 v17, v1
	v_lshl_add_u64 v[2:3], v[2:3], 0, v[16:17]
	v_add_co_u32_e32 v4, vcc, 0x8000, v2
	v_alignbit_b32 v0, v11, v10, 15
	s_nop 0
	v_addc_co_u32_e32 v5, vcc, 0, v3, vcc
	global_load_dword v8, v[2:3], off
	global_load_dword v9, v[4:5], off
	v_lshl_or_b32 v0, v0, 4, v20
	v_lshl_add_u64 v[4:5], v[0:1], 2, s[16:17]
	v_cmp_eq_u32_e32 vcc, v21, v20
	v_mov_b32_e32 v0, 0
	v_mov_b32_e32 v16, 0
	s_and_saveexec_b64 s[24:25], vcc
	s_cbranch_execz .LBB0_353
	global_load_dword v16, v[4:5], off
